# second sample of the same file
# baseline (speedup 1.0000x reference)
; #define LAS __attribute__((address_space(3)))
; __device__ __forceinline__ TItem setup_item(const Params& p, int it) {
;   const int n_win = DEPTH * 16 * 58;
;   const int n_wout = DEPTH * 16 * 16;
;   const int n_w1 = DEPTH * 32 * 2;
;   const int n_w2 = DEPTH * 2 * 1;
;   TItem t;
;   int i = it;
;   if (i < n_win) {
;     int l = i / (16 * 58); int r = i % (16 * 58); int nt = r / 16, kt = r % 16;
;     t.src = p.w_in + (size_t)l * DM * INC; t.dst = P_WIN_T + (size_t)l * HS * DM; t.K = DM; t.N = INC; t.k0 = kt * 64; t.n0 = nt * 64;
;     return t;
;   }
;   i -= n_win;
;   if (i < n_wout) {
;     int l = i / 256; int r = i % 256; int nt = r / 16, kt = r % 16;
;     t.src = p.w_out + (size_t)l * DM * DM; t.dst = P_WOUT_T + (size_t)l * DM * DM; t.K = DM; t.N = DM; t.k0 = kt * 64; t.n0 = nt * 64;
;     return t;
;   }
;   i -= n_wout;
;   if (i < 2 * n_w1) {
;     int which = i / n_w1; int r = i % n_w1; int l = r / 64; r %= 64; int nt = r / 32, kt = r % 32;
;     t.src = (which ? p.wv1 : p.wk1) + (size_t)l * 2048 * 128; t.dst = (which ? P_WV1_T : P_WK1_T) + (size_t)l * 128 * 2048;
;     t.K = 2048; t.N = 128; t.k0 = kt * 64; t.n0 = nt * 64;
;     return t;
;   }
;   i -= 2 * n_w1;
;   {
;     int which = i / n_w2; int r = i % n_w2; int l = r / 2; int kt = r % 2;
;     t.src = (which ? p.wv2 : p.wk2) + (size_t)l * 128 * 64; t.dst = (which ? P_WV2_T : P_WK2_T) + (size_t)l * 64 * 128;
;     t.K = 128; t.N = 64; t.k0 = kt * 64; t.n0 = 0;
;   }
;   return t;
; }
; __global__ void __launch_bounds__(256, 2) hybrid_megakernel(Params p, int ph_lo, int ph_hi) {
;     ...
;   __shared__ uint4 xb_words;
;   if (threadIdx.x == 0) xb_words = make_uint4(0u, 0u, 0u, 0u);
;   __syncthreads();
;   XcdBarrier xb = xcd_barrier_post((unsigned*)P_CTR, (volatile LAS unsigned*)&xb_words);
;   for (int ph = ph_lo; ph < ph_hi; ++ph) {
;     if (ph == 1) continue;
;     run_phase(p, ph, smem);
;     if (ph + 1 < ph_hi) {
;       if (ph_hi > 1000) cg::this_grid().sync();
;       xcd_barrier(xb);
;     }
;   }
.LBB0_5:
	s_or_b64 exec, exec, s[2:3]
	s_load_dwordx2 s[52:53], s[0:1], 0x98
	s_waitcnt lgkmcnt(0)
	s_cmp_ge_i32 s52, s53
	s_cbranch_scc1 .LBB0_563
	s_load_dwordx16 s[36:51], s[0:1], 0x0
	s_load_dwordx16 s[56:71], s[0:1], 0x40
	s_add_u32 s0, s0, 0xa0
	s_addc_u32 s1, s1, 0
	v_writelane_b32 v253, s0, 3
	v_mov_b32_e32 v1, 0x1280
	s_mov_b32 s7, 0x2904400
	v_writelane_b32 v253, s1, 4
	s_mov_b32 s11, 0x2504400
	v_readlane_b32 s17, v253, 0
	s_lshl_b32 s0, s17, 2
	s_cmpk_lt_i32 s17, 0x1490
	v_writelane_b32 v253, s0, 5
	s_cselect_b64 s[0:1], -1, 0
	v_writelane_b32 v253, s0, 6
	s_cmpk_gt_i32 s17, 0xe7f
	v_sub_co_u32_e32 v1, vcc, s17, v1
	v_writelane_b32 v253, s1, 7
	s_cselect_b64 s[0:1], -1, 0
	v_writelane_b32 v253, s0, 8
	s_mov_b32 s87, 0
	v_writelane_b32 v255, s87, 63
	v_mbcnt_lo_u32_b32 v2, -1, 0
	v_writelane_b32 v253, s1, 9
	s_xor_b64 s[0:1], vcc, -1
	v_writelane_b32 v253, s0, 10
	s_cmpk_lt_u32 s17, 0x1480
	v_mbcnt_hi_u32_b32 v215, -1, v2
	v_writelane_b32 v253, s1, 11
	s_cselect_b64 s[0:1], -1, 0
	s_bfe_u32 s2, s17, 0x20001
	s_lshl_b32 s18, s17, 6
	s_and_b32 s3, s17, 0x7ffffff8
	s_lshl_b32 s4, s2, 15
	s_cmpk_eq_i32 s3, 0x1480
	s_waitcnt lgkmcnt(0)
	s_cselect_b32 s5, s66, s70
	s_cselect_b32 s3, s67, s71
	s_cselect_b32 s7, s7, 0x2914400
	s_add_u32 s8, s5, s4
	s_addc_u32 s3, s3, 0
	s_add_u32 s4, s88, s7
	s_addc_u32 s5, s89, 0
	s_lshl_b32 s2, s2, 14
	s_add_u32 s7, s4, s2
	v_readfirstlane_b32 s2, v1
	s_addc_u32 s9, s5, 0
	s_bfe_u32 s4, s2, 0x20006
	s_lshl_b32 s5, s4, 20
	s_cmpk_lt_u32 s2, 0x100
	s_cselect_b32 s2, s65, s69
	v_writelane_b32 v253, s56, 12
	s_cselect_b32 s10, s64, s68
	s_cselect_b32 s11, s11, 0x2704400
	v_writelane_b32 v253, s57, 13
	v_writelane_b32 v253, s58, 14
	v_writelane_b32 v253, s59, 15
	v_writelane_b32 v253, s60, 16
	v_writelane_b32 v253, s61, 17
	v_writelane_b32 v253, s62, 18
	v_writelane_b32 v253, s63, 19
	v_writelane_b32 v253, s64, 20
	v_writelane_b32 v253, s65, 21
	s_add_u32 s10, s10, s5
	v_writelane_b32 v253, s66, 22
	s_addc_u32 s12, s2, 0
	v_writelane_b32 v253, s67, 23
	s_add_u32 s2, s88, s11
	v_writelane_b32 v253, s68, 24
	s_addc_u32 s5, s89, 0
	s_lshl_b32 s4, s4, 19
	v_writelane_b32 v253, s69, 25
	s_add_u32 s11, s2, s4
	v_writelane_b32 v253, s70, 26
	s_addc_u32 s13, s5, 0
	s_add_i32 s14, s17, 0xfffff180
	v_writelane_b32 v253, s71, 27
	s_lshl_b32 s2, s17, 1
	s_lshr_b32 s86, s14, 8
	v_writelane_b32 v253, s2, 28
	s_and_b32 s2, s2, 64
	s_lshl_b64 s[4:5], s[86:87], 22
	s_add_u32 s4, s42, s4
	s_addc_u32 s5, s43, s5
	v_writelane_b32 v253, s4, 29
	s_add_u32 s15, s88, 0x1d04400
	s_addc_u32 s16, s89, 0
	v_writelane_b32 v253, s5, 30
	s_lshl_b64 s[4:5], s[86:87], 21
	v_writelane_b32 v253, s15, 31
	s_add_u32 s4, s15, s4
	v_writelane_b32 v253, s16, 32
	s_addc_u32 s5, s16, s5
	v_writelane_b32 v253, s4, 33
	v_lshrrev_b32_e32 v1, 20, v0
	v_lshrrev_b32_e32 v0, 10, v0
	v_writelane_b32 v253, s5, 34
	s_and_b32 s4, s18, 0x3c0
	v_writelane_b32 v253, s4, 35
	s_lshl_b32 s4, s14, 2
	v_writelane_b32 v253, s14, 36
	s_and_b32 s4, s4, 0x3c0
	v_writelane_b32 v253, s4, 37
	s_mul_hi_i32 s4, s17, 0x8d3dcb09
	s_add_i32 s4, s4, s17
	s_lshr_b32 s5, s4, 31
	s_ashr_i32 s4, s4, 9
	s_add_i32 s4, s4, s5
	s_mul_i32 s5, s4, 0x3a0
	s_sub_i32 s5, s17, s5
	s_bfe_u32 s14, s5, 0x4001b
	s_add_i32 s14, s5, s14
	s_sext_i32_i16 s15, s14
	s_and_b32 s14, s14, 0xfff0
	s_sub_i32 s5, s5, s14
	s_mul_i32 s16, s4, 0xe18000
	s_add_u32 s24, s40, s16
	v_writelane_b32 v253, s36, 38
	s_mul_hi_i32 s14, s4, 0xe18000
	s_addc_u32 s25, s41, s14
	v_writelane_b32 v253, s37, 39
	v_writelane_b32 v253, s38, 40
	v_writelane_b32 v253, s39, 41
	v_writelane_b32 v253, s40, 42
	v_writelane_b32 v253, s41, 43
	v_writelane_b32 v253, s42, 44
	v_writelane_b32 v253, s43, 45
	v_writelane_b32 v253, s44, 46
	v_writelane_b32 v253, s45, 47
	v_writelane_b32 v253, s46, 48
	v_writelane_b32 v253, s47, 49
	v_writelane_b32 v253, s48, 50
	v_writelane_b32 v253, s49, 51
	v_writelane_b32 v253, s50, 52
	v_writelane_b32 v253, s51, 53
	v_writelane_b32 v253, s24, 54
	s_add_u32 s16, s88, 0x4400
	s_addc_u32 s19, s89, 0
	v_writelane_b32 v253, s25, 55
	s_mul_hi_i32 s14, s4, 0x740000
	s_mul_i32 s4, s4, 0x740000
	v_writelane_b32 v253, s16, 56
	s_add_u32 s24, s16, s4
	v_writelane_b32 v253, s19, 57
	s_addc_u32 s25, s19, s14
	s_sext_i32_i16 s5, s5
	v_writelane_b32 v253, s24, 58
	s_lshl_b32 s4, s5, 6
	v_or_b32_e32 v0, v0, v1
	v_writelane_b32 v253, s25, 59
	v_writelane_b32 v253, s4, 60
	s_lshl_b32 s4, s15, 2
	s_andn2_b32 s4, s4, 63
	s_cmp_eq_u32 s17, 0
	v_writelane_b32 v253, s4, 61
	s_cselect_b64 s[4:5], -1, 0
	v_writelane_b32 v253, s4, 62
	v_and_b32_e32 v216, 64, v215
	v_mov_b32_e32 v1, 0
	v_writelane_b32 v253, s5, 63
	s_add_u32 s4, s88, 0x4000
	s_addc_u32 s5, s89, 0
	s_add_u32 s36, s88, 0x2924400
	s_addc_u32 s37, s89, 0
	v_writelane_b32 v254, s4, 0
	s_cmpk_lt_i32 s17, 0x200
	v_mov_b32_e32 v211, 0x358637bd
	v_writelane_b32 v254, s5, 1
	s_cselect_b64 s[4:5], -1, 0
	v_writelane_b32 v254, s4, 2
	v_mov_b32_e32 v212, 0x12080
	s_mov_b32 s27, 0x20000
	v_writelane_b32 v254, s5, 3
	s_add_u32 s4, s88, 0x4924400
	s_addc_u32 s33, s89, 0
	v_writelane_b32 v254, s4, 4
	s_add_u32 s4, s88, 0xd124400
	s_addc_u32 s5, s89, 0
	v_writelane_b32 v254, s4, 5
	s_brev_b32 s26, -2
	v_add_u32_e32 v217, 64, v216
	v_writelane_b32 v254, s5, 6
	s_add_u32 s4, s88, 0xd164400
	s_addc_u32 s5, s89, 0
; #define LAS __attribute__((address_space(3)))
; __device__ __forceinline__ XcdBarrier xcd_barrier_post(unsigned* bar, volatile LAS unsigned* st) {
;     XcdBarrier b; b.bar = bar; b.x = xb_xcc_id(); b.st = st;
;     if (threadIdx.x == 0) (void)xb_add(&bar[XB_XCNT(b.x)], 1u);
;     return b;
; }
; __device__ __forceinline__ void xcd_barrier_complete(unsigned* bar, unsigned x, unsigned& nloc, unsigned& nx) {
;     const unsigned G = gridDim.x * gridDim.y * gridDim.z;
;     unsigned sum, cnt, mine, sp = 0u;
;     for (;;) {
;         sum = 0u; cnt = 0u; mine = 0u;
; #pragma unroll
;         for (unsigned j = 0; j < 16; ++j) { const unsigned c = xb_ld(&bar[XB_XCNT(j)]); sum += c; cnt += (c > 0u) ? 1u : 0u; mine = (j == x) ? c : mine; }
;         if (sum == G) break;
;         __builtin_amdgcn_s_sleep(1);
;         if ((++sp & 255u) == 0u) { if (xb_ld(&bar[XB_TMO])) break; if (sp > XB_SPIN_CAP) { atomicAdd(&bar[XB_TMO], 1u); break; } }
;     }
;     nloc = mine > 0u ? mine : 1u; nx = cnt > 0u ? cnt : 1u;
; }
; __device__ __forceinline__ void xcd_barrier(const XcdBarrier& b) {
;     asm volatile("s_waitcnt vmcnt(0)" ::: "memory");
;     __syncthreads();
;     if (threadIdx.x == 0) {
;         unsigned* bar = b.bar;
;         __builtin_amdgcn_s_waitcnt(0);
;         unsigned nloc = b.st[0], nx = b.st[1];
;         if (nloc == 0u) { xcd_barrier_complete(bar, b.x, nloc, nx); b.st[0] = nloc; b.st[1] = nx; }
;         const unsigned old = xb_add(&bar[XB_XSUB(b.x)], 1u);
;         const unsigned gen = old / nloc;
;         if (old + 1u == (gen + 1u) * nloc) {
;             __builtin_amdgcn_fence(__ATOMIC_RELEASE, "agent");
;             asm volatile("s_waitcnt vmcnt(0)" ::: "memory");
;             const unsigned og = xb_add(&bar[XB_TOP], 1u);
;             const unsigned tg = og / nx;
;             if (og + 1u == (tg + 1u) * nx) xb_add(&bar[XB_TOPGEN], 1u);
;             else XB_SPIN(xb_ld(&bar[XB_TOPGEN]) == tg, bar);
;             __builtin_amdgcn_fence(__ATOMIC_ACQUIRE, "agent");
;             xb_add(&bar[XB_XGEN(b.x)], 1u);
;             asm volatile("s_waitcnt vmcnt(0)" ::: "memory");
;         } else {
;             XB_SPIN(xb_ld(&bar[XB_XGEN(b.x)]) == gen, bar);
;             __builtin_amdgcn_fence(__ATOMIC_ACQUIRE, "agent");
;             asm volatile("s_waitcnt vmcnt(0)" ::: "memory");
;         }
;     }
;     __syncthreads();
	v_writelane_b32 v254, s4, 7
	v_xor_b32_e32 v250, 1, v215
	v_xor_b32_e32 v251, 2, v215
	v_writelane_b32 v254, s5, 8
	s_add_u32 s4, s88, 0xbd24400
	v_writelane_b32 v254, s4, 9
	s_addc_u32 s4, s89, 0
	s_add_i32 s14, s17, 0xffffff00
	s_cmpk_lt_i32 s17, 0x100
	v_writelane_b32 v254, s4, 10
	s_cselect_b64 s[4:5], -1, 0
	v_writelane_b32 v254, s4, 11
	v_xor_b32_e32 v252, 4, v215
	v_xor_b32_e32 v214, 16, v215
	v_writelane_b32 v254, s5, 12
	s_and_b64 s[4:5], s[4:5], exec
	s_cselect_b32 s4, 0x200, s14
	s_cmpk_lt_u32 s17, 0x740
	v_writelane_b32 v254, s4, 13
	s_cselect_b64 s[4:5], -1, 0
	v_writelane_b32 v254, s4, 14
	v_xor_b32_e32 v229, 32, v215
	v_mov_b32_e32 v213, 0x42800000
	v_writelane_b32 v254, s5, 15
	s_lshl_b32 s4, s17, 3
	s_and_b32 s4, s4, 56
	v_writelane_b32 v254, s4, 16
	s_lshr_b32 s4, s17, 3
	s_cmpk_lt_u32 s17, 0x200
	v_writelane_b32 v254, s4, 17
	s_cselect_b64 s[4:5], -1, 0
	v_writelane_b32 v254, s4, 18
	s_cmpk_gt_i32 s53, 0x3e8
	v_mov_b32_e32 v227, 0x12000
	v_writelane_b32 v254, s5, 19
	s_cselect_b64 s[4:5], -1, 0
	v_writelane_b32 v254, s4, 20
	v_mov_b32_e32 v226, 0xf149f2ca
	v_mov_b32_e32 v228, 0x1d00
	v_writelane_b32 v254, s5, 21
	s_add_u32 s4, s88, 0x200
	s_addc_u32 s5, s89, 0
	v_writelane_b32 v254, s4, 22
	s_movk_i32 s74, 0x3fff
	s_movk_i32 s75, 0x210
	v_writelane_b32 v254, s5, 23
	s_add_u32 s4, s88, 0x1000
	s_addc_u32 s5, s89, 0
	v_writelane_b32 v254, s4, 24
	s_movk_i32 s15, 0x90
	s_brev_b32 s34, 1
	v_writelane_b32 v254, s5, 25
	s_add_u32 s4, s88, 0x1100
	s_addc_u32 s5, s89, 0
	v_writelane_b32 v254, s4, 26
	s_mov_b32 s77, 0x40000
	s_mov_b32 s78, 0x60000
	v_writelane_b32 v254, s5, 27
	s_add_u32 s4, s88, 0x1200
	s_addc_u32 s5, s89, 0
	v_writelane_b32 v254, s4, 28
	s_mov_b32 s14, 0x3e38aa3b
	s_mov_b32 s28, 0x3f803f80
	v_writelane_b32 v254, s5, 29
	s_add_u32 s4, s88, 0x1300
	s_addc_u32 s5, s89, 0
	v_writelane_b32 v254, s4, 30
	s_cmp_eq_u32 s6, 15
	s_nop 0
	v_writelane_b32 v254, s5, 31
	s_cselect_b64 s[4:5], -1, 0
	v_writelane_b32 v254, s4, 32
	s_cmp_eq_u32 s6, 14
	s_nop 0
	v_writelane_b32 v254, s5, 33
	s_cselect_b64 s[4:5], -1, 0
	v_writelane_b32 v254, s4, 34
	s_cmp_eq_u32 s6, 13
	s_nop 0
	v_writelane_b32 v254, s5, 35
	s_cselect_b64 s[4:5], -1, 0
	v_writelane_b32 v254, s4, 36
	s_cmp_eq_u32 s6, 12
	s_nop 0
	v_writelane_b32 v254, s5, 37
	s_cselect_b64 s[4:5], -1, 0
	v_writelane_b32 v254, s4, 38
	s_cmp_eq_u32 s6, 11
	s_nop 0
	v_writelane_b32 v254, s5, 39
	s_cselect_b64 s[4:5], -1, 0
	v_writelane_b32 v254, s4, 40
	s_cmp_eq_u32 s6, 10
	s_nop 0
	v_writelane_b32 v254, s5, 41
	s_cselect_b64 s[4:5], -1, 0
	v_writelane_b32 v254, s4, 42
	s_cmp_eq_u32 s6, 9
	s_nop 0
	v_writelane_b32 v254, s5, 43
	s_cselect_b64 s[4:5], -1, 0
	v_writelane_b32 v254, s4, 44
	s_cmp_eq_u32 s6, 8
	s_nop 0
	v_writelane_b32 v254, s5, 45
	s_cselect_b64 s[4:5], -1, 0
	v_writelane_b32 v254, s4, 46
	s_cmp_eq_u32 s6, 7
	s_nop 0
	v_writelane_b32 v254, s5, 47
	s_cselect_b64 s[4:5], -1, 0
	v_writelane_b32 v254, s4, 48
	s_cmp_eq_u32 s6, 6
	s_nop 0
	v_writelane_b32 v254, s5, 49
	s_cselect_b64 s[4:5], -1, 0
	v_writelane_b32 v254, s4, 50
	s_cmp_eq_u32 s6, 5
	s_nop 0
	v_writelane_b32 v254, s5, 51
	s_cselect_b64 s[4:5], -1, 0
	v_writelane_b32 v254, s4, 52
	s_cmp_eq_u32 s6, 4
	s_nop 0
	v_writelane_b32 v254, s5, 53
	s_cselect_b64 s[4:5], -1, 0
	v_writelane_b32 v254, s4, 54
	s_cmp_eq_u32 s6, 3
	s_nop 0
	v_writelane_b32 v254, s5, 55
	s_cselect_b64 s[4:5], -1, 0
	v_writelane_b32 v254, s4, 56
	s_cmp_eq_u32 s6, 2
	s_nop 0
	v_writelane_b32 v254, s5, 57
	s_cselect_b64 s[4:5], -1, 0
	v_writelane_b32 v254, s4, 58
	s_cmp_eq_u32 s6, 1
	s_nop 0
	v_writelane_b32 v254, s5, 59
	s_cselect_b64 s[4:5], -1, 0
	v_writelane_b32 v254, s4, 60
	s_cmp_eq_u32 s6, 0
	s_nop 0
	v_writelane_b32 v254, s5, 61
	s_cselect_b64 s[4:5], -1, 0
	v_writelane_b32 v254, s4, 62
	s_nop 1
	v_writelane_b32 v254, s5, 63
	s_lshl_b32 s4, s6, 8
	s_add_u32 s4, s88, s4
	s_addc_u32 s5, s89, 0
	s_add_u32 s16, s4, 0x1400
	s_addc_u32 s17, s5, 0
	v_writelane_b32 v255, s16, 0
	s_add_u32 s4, s4, 0x2400
	s_addc_u32 s5, s5, 0
	v_writelane_b32 v255, s17, 1
	v_writelane_b32 v255, s4, 2
	s_mov_b32 s16, 0xf0c9f2ca
	s_movk_i32 s17, 0x31f
	v_writelane_b32 v255, s5, 3
	s_add_u32 s4, s88, 0x3400
	s_addc_u32 s5, s89, 0
	v_writelane_b32 v255, s4, 4
	s_nop 1
	v_writelane_b32 v255, s5, 5
	s_add_u32 s4, s88, 0x3500
	s_addc_u32 s5, s89, 0
	v_writelane_b32 v255, s4, 6
	s_nop 1
	v_writelane_b32 v255, s5, 7
	s_and_b64 s[4:5], s[0:1], exec
	s_cselect_b32 s5, s12, s3
	s_cselect_b32 s4, s10, s8
	v_writelane_b32 v255, s4, 8
	s_movk_i32 s3, 0x800
	s_cselect_b32 s3, s3, 0x80
	v_writelane_b32 v255, s5, 9
	s_cselect_b32 s5, s13, s9
	s_cselect_b32 s4, s11, s7
	v_writelane_b32 v255, s4, 10
	s_movk_i32 s10, 0x200
	s_movk_i32 s11, 0x80
	v_writelane_b32 v255, s5, 11
	v_writelane_b32 v255, s3, 12
	s_cselect_b32 s3, 0x80, 64
	v_writelane_b32 v255, s3, 13
	s_cselect_b32 s3, 0x7c0, 64
	s_and_b32 s3, s18, s3
	s_and_b64 s[0:1], s[0:1], exec
	v_writelane_b32 v255, s18, 14
	s_movk_i32 s0, 0x3ff
	v_writelane_b32 v255, s3, 15
	v_and_or_b32 v0, v0, s0, v210
	s_cselect_b32 s0, s2, 0
	v_writelane_b32 v255, s0, 16
	v_cmp_eq_u32_e64 s[0:1], 0, v0
	s_movk_i32 s3, 0x1d00
	s_movk_i32 s4, 0x2ff
	v_writelane_b32 v255, s0, 17
	s_movk_i32 s5, 0x110
	s_mov_b32 s2, -1.0
	s_movk_i32 s13, 0xfdff
	v_writelane_b32 v255, s1, 18
	s_branch .LBB0_10

; __global__ void __launch_bounds__(256, 2) hybrid_megakernel(Params p, int ph_lo, int ph_hi) {
;     ...
;   for (int ph = ph_lo; ph < ph_hi; ++ph) {
;     if (ph == 1) continue;
;     run_phase(p, ph, smem);
;     if (ph + 1 < ph_hi) {
;       if (ph_hi > 1000) cg::this_grid().sync();
;       xcd_barrier(xb);
;     }
;   }
.LBB0_9:
	v_readlane_b32 s0, v255, 63
	s_lshr_b32 s1, 0x10840, s52
	s_and_b32 s1, s1, 1
	s_cmp_lt_u32 s0, 1
	s_cselect_b32 s1, s1, 0
	s_add_u32 s0, s0, 1
	s_cmp_lg_u32 s1, 0
	s_cselect_b32 s0, s0, 0
	s_cselect_b32 s12, s52, s12
	v_writelane_b32 v255, s0, 63
	s_cmp_ge_i32 s12, s53
	s_mov_b32 s52, s12
	s_cbranch_scc1 .LBB0_563
